# GU GEMM epilogue: per-M-tile RMSNorm row scales cached in spare LDS (tagged by phase and M-tile); on a hit the 8 ssq loads and the vmcnt(0) that also drained the next tile's LDS-DMA prefetch are skipp
# speedup vs baseline: 1.0103x; 1.0103x over previous
; __device__ __forceinline__ void row_rs8(const float* __restrict__ ssq, int row0, int fq, float (&rs)[2][4]) {
;     f32x4 s4[2][4];
; #pragma unroll
;     for (int ai = 0; ai < 2; ++ai)
; #pragma unroll
;         for (int m = 0; m < 4; ++m) s4[ai][m] = *(const f32x4*)(ssq + (size_t)(row0 + ai * HALF + m * 16) * 16 + 4 * fq);
; #pragma unroll
;     for (int ai = 0; ai < 2; ++ai)
; #pragma unroll
;         for (int m = 0; m < 4; ++m) { float s = (s4[ai][m][0] + s4[ai][m][1]) + (s4[ai][m][2] + s4[ai][m][3]); s += __shfl_xor(s, 16); s += __shfl_xor(s, 32); rs[ai][m] = rsqrtf(s * (1.0f / 1024.0f) + 1e-6f); }
; }
;     __device__ __forceinline__ void operator()(const f32x4 (&acc)[2][2][4][2], const Unit& u, int wr, int wc, int fr, int fq) const {
;         float rs8[2][4]; row_rs8(ssq, u.pm * BM + wr * 64 + fr, fq, rs8);
.LBB0_571:
	s_lshl_b32 s47, s40, 8
	v_add_u32_e32 v180, s47, v186
	s_lshl_b32 s54, s8, 24
	s_or_b32 s54, s54, s47
	s_or_b32 s54, s54, 0x5a
	v_lshrrev_b32_e32 v181, 4, v186
	v_and_b32_e32 v181, 4, v181
	v_add_u32_e32 v181, 0x20400, v181
	ds_read_b32 v179, v181
	s_waitcnt lgkmcnt(0)
	v_readfirstlane_b32 s55, v179
	s_nop 3
	s_cmp_eq_u32 s55, s54
	s_cselect_b32 s55, 1, 0
	s_cbranch_scc0 .Lgu_ld
	v_add_u32_e32 v178, 0x80, v180
	v_add_u32_e32 v176, 0x90, v180
	v_add_u32_e32 v174, 0xa0, v180
	v_add_u32_e32 v172, 0xb0, v180
	s_branch .Lgu_ldone
.Lgu_ld:
	v_ashrrev_i32_e32 v181, 31, v180
	v_lshlrev_b64 v[136:137], 6, v[180:181]
	v_lshl_add_u64 v[136:137], v[166:167], 0, v[136:137]
	global_load_dwordx4 v[182:185], v[136:137], off
	v_or_b32_e32 v136, 16, v180
	v_ashrrev_i32_e32 v137, 31, v136
	v_lshlrev_b64 v[136:137], 6, v[136:137]
	v_lshl_add_u64 v[136:137], v[166:167], 0, v[136:137]
	global_load_dwordx4 v[192:195], v[136:137], off
	v_or_b32_e32 v136, 32, v180
	v_ashrrev_i32_e32 v137, 31, v136
	v_lshlrev_b64 v[136:137], 6, v[136:137]
	v_lshl_add_u64 v[136:137], v[166:167], 0, v[136:137]
	global_load_dwordx4 v[156:159], v[136:137], off
	v_or_b32_e32 v136, 48, v180
	v_ashrrev_i32_e32 v137, 31, v136
	v_lshlrev_b64 v[136:137], 6, v[136:137]
	v_lshl_add_u64 v[136:137], v[166:167], 0, v[136:137]
	global_load_dwordx4 v[152:155], v[136:137], off
	v_add_u32_e32 v178, 0x80, v180
	v_ashrrev_i32_e32 v179, 31, v178
	v_lshlrev_b64 v[136:137], 6, v[178:179]
	v_add_u32_e32 v176, 0x90, v180
	v_lshl_add_u64 v[136:137], v[166:167], 0, v[136:137]
	v_ashrrev_i32_e32 v177, 31, v176
	global_load_dwordx4 v[148:151], v[136:137], off
	v_lshlrev_b64 v[136:137], 6, v[176:177]
	v_lshl_add_u64 v[136:137], v[166:167], 0, v[136:137]
	global_load_dwordx4 v[144:147], v[136:137], off
	v_add_u32_e32 v174, 0xa0, v180
	v_ashrrev_i32_e32 v175, 31, v174
	v_lshlrev_b64 v[136:137], 6, v[174:175]
	v_add_u32_e32 v172, 0xb0, v180
	v_lshl_add_u64 v[136:137], v[166:167], 0, v[136:137]
	v_ashrrev_i32_e32 v173, 31, v172
	global_load_dwordx4 v[140:143], v[136:137], off
	v_lshlrev_b64 v[136:137], 6, v[172:173]
	v_lshl_add_u64 v[136:137], v[166:167], 0, v[136:137]
	global_load_dwordx4 v[136:139], v[136:137], off
.Lgu_ldone:
	v_and_b32_e32 v175, 64, v234
	v_xor_b32_e32 v173, 16, v234
	v_add_u32_e32 v177, 64, v175
	v_cmp_lt_i32_e32 vcc, v173, v177
	s_mov_b32 s40, 0x358637bd
	s_mov_b32 s54, 0x3a800000
	v_cndmask_b32_e32 v173, v234, v173, vcc
	v_lshlrev_b32_e32 v175, 2, v173
	v_xor_b32_e32 v173, 32, v234
	v_cmp_lt_i32_e32 vcc, v173, v177
	v_mul_f32_e32 v123, v127, v123
	s_movk_i32 s75, 0x1600
	v_cndmask_b32_e32 v173, v234, v173, vcc
	v_lshlrev_b32_e32 v173, 2, v173
	s_mov_b32 s78, 0x6001000
	v_readlane_b32 s79, v254, 43
	s_mov_b32 s6, 0x2aaaaaab
	s_cmp_eq_u32 s55, 1
	s_cbranch_scc1 .Lgu_nw
	s_waitcnt vmcnt(0)
.Lgu_nw:
	v_mov_b32_e32 v196, v183
	v_mov_b32_e32 v197, v184
	v_mov_b32_e32 v183, v185
	v_pk_add_f32 v[182:183], v[196:197], v[182:183]
	v_mov_b32_e32 v184, v193
	v_mov_b32_e32 v185, v194
	v_mov_b32_e32 v193, v195
	v_pk_add_f32 v[184:185], v[184:185], v[192:193]
	v_mov_b32_e32 v193, v182
	v_mov_b32_e32 v192, v184
	v_mov_b32_e32 v182, v185
	v_pk_add_f32 v[182:183], v[192:193], v[182:183]
	ds_bpermute_b32 v185, v175, v183
	ds_bpermute_b32 v184, v175, v182
	v_mov_b32_e32 v192, v157
	v_mov_b32_e32 v193, v158
	v_mov_b32_e32 v157, v159
	v_mov_b32_e32 v158, v153
	v_mov_b32_e32 v159, v154
	v_mov_b32_e32 v153, v155
	v_pk_add_f32 v[156:157], v[192:193], v[156:157]
	v_pk_add_f32 v[152:153], v[158:159], v[152:153]
	s_waitcnt lgkmcnt(0)
	v_pk_add_f32 v[182:183], v[182:183], v[184:185]
	v_mov_b32_e32 v154, v152
	v_mov_b32_e32 v155, v156
	v_mov_b32_e32 v156, v153
	ds_bpermute_b32 v185, v173, v183
	ds_bpermute_b32 v184, v173, v182
	v_pk_add_f32 v[152:153], v[154:155], v[156:157]
	ds_bpermute_b32 v155, v175, v153
	ds_bpermute_b32 v154, v175, v152
	v_mov_b32_e32 v156, v149
	v_mov_b32_e32 v157, v150
	v_mov_b32_e32 v149, v151
	v_mov_b32_e32 v150, v145
	v_mov_b32_e32 v151, v146
	v_mov_b32_e32 v145, v147
	s_waitcnt lgkmcnt(2)
	v_pk_add_f32 v[182:183], v[182:183], v[184:185]
	v_mov_b64_e32 v[184:185], s[40:41]
	v_pk_add_f32 v[148:149], v[156:157], v[148:149]
	v_pk_add_f32 v[144:145], v[150:151], v[144:145]
	v_pk_fma_f32 v[182:183], v[182:183], s[54:55], v[184:185] op_sel_hi:[1,0,0]
	s_waitcnt lgkmcnt(0)
	v_pk_add_f32 v[152:153], v[152:153], v[154:155]
	v_mov_b32_e32 v146, v144
	v_mov_b32_e32 v147, v148
	v_mov_b32_e32 v148, v145
	v_mul_f32_e32 v177, 0x4b800000, v183
	v_cmp_gt_f32_e64 s[40:41], s22, v183
	ds_bpermute_b32 v155, v173, v153
	ds_bpermute_b32 v154, v173, v152
	v_pk_add_f32 v[144:145], v[146:147], v[148:149]
	v_cndmask_b32_e64 v177, v183, v177, s[40:41]
	ds_bpermute_b32 v147, v175, v145
	ds_bpermute_b32 v146, v175, v144
	v_rsq_f32_e32 v177, v177
	v_mov_b32_e32 v148, v141
	v_mov_b32_e32 v149, v142
	v_mov_b32_e32 v141, v143
	v_mov_b32_e32 v142, v137
	v_mov_b32_e32 v143, v138
	v_mov_b32_e32 v137, v139
	s_waitcnt lgkmcnt(2)
	v_pk_add_f32 v[152:153], v[152:153], v[154:155]
	v_pk_add_f32 v[140:141], v[148:149], v[140:141]
	v_pk_add_f32 v[136:137], v[142:143], v[136:137]
	v_mul_f32_e32 v179, 0x45800000, v177
	v_pk_fma_f32 v[152:153], v[152:153], s[54:55], v[184:185] op_sel_hi:[1,0,0]
	s_waitcnt lgkmcnt(0)
	v_pk_add_f32 v[144:145], v[144:145], v[146:147]
	v_mov_b32_e32 v138, v136
	v_mov_b32_e32 v139, v140
	v_mov_b32_e32 v140, v137
	v_cmp_gt_f32_e32 vcc, s22, v182
	v_cndmask_b32_e64 v183, v177, v179, s[40:41]
	v_mul_f32_e32 v177, 0x4b800000, v182
	v_mul_f32_e32 v154, 0x4b800000, v153
	v_cmp_gt_f32_e64 s[40:41], s22, v153
	ds_bpermute_b32 v147, v173, v145
	ds_bpermute_b32 v146, v173, v144
	v_pk_add_f32 v[136:137], v[138:139], v[140:141]
	v_cndmask_b32_e32 v177, v182, v177, vcc
	v_cndmask_b32_e64 v153, v153, v154, s[40:41]
	ds_bpermute_b32 v139, v175, v137
	ds_bpermute_b32 v138, v175, v136
	v_rsq_f32_e32 v177, v177
	v_rsq_f32_e32 v153, v153
	s_waitcnt lgkmcnt(2)
; __device__ __forceinline__ unsigned cvt_pk_bf16(float lo, float hi) { unsigned r; asm volatile("v_cvt_pk_bf16_f32 %0, %1, %2" : "=v"(r) : "v"(lo), "v"(hi)); return r; }
; __device__ __forceinline__ void row_rs8(const float* __restrict__ ssq, int row0, int fq, float (&rs)[2][4]) {
;     ...
;         for (int m = 0; m < 4; ++m) { float s = (s4[ai][m][0] + s4[ai][m][1]) + (s4[ai][m][2] + s4[ai][m][3]); s += __shfl_xor(s, 16); s += __shfl_xor(s, 32); rs[ai][m] = rsqrtf(s * (1.0f / 1024.0f) + 1e-6f); }
; }
;     __device__ __forceinline__ void operator()(const f32x4 (&acc)[2][2][4][2], const Unit& u, int wr, int wc, int fr, int fq) const {
;         float rs8[2][4]; row_rs8(ssq, u.pm * BM + wr * 64 + fr, fq, rs8);
; #pragma unroll
;         for (int ai = 0; ai < 2; ++ai)
; #pragma unroll
;             for (int m = 0; m < 4; ++m) {
;                 const int row = u.pm * BM + ai * HALF + wr * 64 + m * 16 + fr;
;                 const float rs = rs8[ai][m], rsl = -1.4426950408889634f * rs, rs2 = rs * rs;
;                 float hv[8];
; #pragma unroll
;                 for (int n = 0; n < 2; ++n) {
;                     const f32x4 ag = acc[ai][0][m][n], au = acc[ai][1][m][n];
;                     const f32x4 ea = ag * rsl, gu = (ag * au) * rs2;
; #pragma unroll
;                     for (int j = 0; j < 4; ++j) hv[4 * n + j] = gu[j] * __builtin_amdgcn_rcpf(1.0f + __builtin_amdgcn_exp2f(ea[j]));
;                 }
;                 u32x4 w; w.x = cvt_pk_bf16(hv[0], hv[1]); w.y = cvt_pk_bf16(hv[2], hv[3]); w.z = cvt_pk_bf16(hv[4], hv[5]); w.w = cvt_pk_bf16(hv[6], hv[7]);
;                 *(u32x4*)(H + (size_t)row * ldh + u.pn * 128 + wc * 32 + 8 * fq) = w;
	v_pk_add_f32 v[144:145], v[144:145], v[146:147]
	v_mov_b32_e32 v182, v126
	v_mul_f32_e32 v179, 0x45800000, v177
	v_mul_f32_e32 v154, 0x45800000, v153
	v_pk_fma_f32 v[144:145], v[144:145], s[54:55], v[184:185] op_sel_hi:[1,0,0]
	s_waitcnt lgkmcnt(0)
	v_pk_add_f32 v[136:137], v[136:137], v[138:139]
	v_cndmask_b32_e32 v181, v177, v179, vcc
	v_cmp_gt_f32_e32 vcc, s22, v152
	v_cndmask_b32_e64 v155, v153, v154, s[40:41]
	v_mul_f32_e32 v153, 0x4b800000, v152
	v_mul_f32_e32 v146, 0x4b800000, v145
	v_cmp_gt_f32_e64 s[40:41], s22, v145
	ds_bpermute_b32 v139, v173, v137
	ds_bpermute_b32 v138, v173, v136
	v_cndmask_b32_e32 v152, v152, v153, vcc
	v_cndmask_b32_e64 v145, v145, v146, s[40:41]
	v_rsq_f32_e32 v152, v152
	v_rsq_f32_e32 v145, v145
	s_waitcnt lgkmcnt(0)
	v_pk_add_f32 v[136:137], v[136:137], v[138:139]
	v_mov_b32_e32 v154, v94
	v_mul_f32_e32 v153, 0x45800000, v152
	v_mul_f32_e32 v146, 0x45800000, v145
	v_pk_fma_f32 v[136:137], v[136:137], s[54:55], v[184:185] op_sel_hi:[1,0,0]
	v_cndmask_b32_e32 v153, v152, v153, vcc
	v_cmp_gt_f32_e32 vcc, s22, v144
	v_cndmask_b32_e64 v147, v145, v146, s[40:41]
	v_mul_f32_e32 v145, 0x4b800000, v144
	v_mul_f32_e32 v138, 0x4b800000, v137
	v_cmp_gt_f32_e64 s[40:41], s22, v137
	v_cndmask_b32_e32 v144, v144, v145, vcc
	v_rsq_f32_e32 v144, v144
	v_cndmask_b32_e64 v137, v137, v138, s[40:41]
	v_rsq_f32_e32 v137, v137
	v_mov_b32_e32 v152, v78
	v_mul_f32_e32 v145, 0x45800000, v144
	v_cndmask_b32_e32 v145, v144, v145, vcc
	v_mul_f32_e32 v138, 0x45800000, v137
	v_cmp_gt_f32_e32 vcc, s22, v136
	v_cndmask_b32_e64 v139, v137, v138, s[40:41]
	v_mul_f32_e32 v137, 0x4b800000, v136
	v_cndmask_b32_e32 v136, v136, v137, vcc
	v_rsq_f32_e32 v136, v136
	v_readlane_b32 s40, v252, 3
	v_readlane_b32 s41, v252, 4
	v_mov_b32_e32 v146, v62
	v_mul_f32_e32 v137, 0x45800000, v136
	v_cndmask_b32_e32 v137, v136, v137, vcc
	s_cmp_eq_u32 s55, 1
	s_mov_b32 s54, 0x20000
	v_lshl_add_u32 v177, v186, 2, s54
	s_cbranch_scc0 .Lgu_store
	ds_read_b32 v183, v177
	ds_read_b32 v181, v177 offset:64
	ds_read_b32 v155, v177 offset:128
	ds_read_b32 v153, v177 offset:192
	ds_read_b32 v147, v177 offset:512
	ds_read_b32 v145, v177 offset:576
	ds_read_b32 v139, v177 offset:640
	ds_read_b32 v137, v177 offset:704
	s_waitcnt lgkmcnt(0)
	s_branch .Lgu_rsdone
.Lgu_store:
	ds_write_b32 v177, v183
	ds_write_b32 v177, v181 offset:64
	ds_write_b32 v177, v155 offset:128
	ds_write_b32 v177, v153 offset:192
	ds_write_b32 v177, v147 offset:512
	ds_write_b32 v177, v145 offset:576
	ds_write_b32 v177, v139 offset:640
	ds_write_b32 v177, v137 offset:704
	s_lshl_b32 s54, s8, 24
	s_or_b32 s54, s54, s47
	s_or_b32 s54, s54, 0x5a
	v_lshrrev_b32_e32 v179, 4, v186
	v_and_b32_e32 v179, 4, v179
	v_add_u32_e32 v179, 0x20400, v179
	v_mov_b32_e32 v175, s54
	s_waitcnt lgkmcnt(0)
	ds_write_b32 v179, v175
.Lgu_rsdone:
	v_mul_f32_e32 v136, 0xbfb8aa3b, v183
	v_pk_mul_f32 v[142:143], v[132:133], v[136:137] op_sel_hi:[1,0]
	v_mul_f32_e32 v132, v132, v128
	v_exp_f32_e32 v128, v142
	v_pk_mul_f32 v[140:141], v[134:135], v[136:137] op_sel_hi:[1,0]
	v_mul_f32_e32 v134, v134, v130
	v_mul_f32_e32 v135, v135, v131
	v_add_f32_e32 v128, 1.0, v128
	v_rcp_f32_e32 v138, v128
	v_exp_f32_e32 v128, v143
	v_pk_mul_f32 v[130:131], v[124:125], v[136:137] op_sel_hi:[1,0]
	v_mul_f32_e32 v124, v124, v120
	v_exp_f32_e32 v120, v130
	v_add_f32_e32 v128, 1.0, v128
	v_rcp_f32_e32 v142, v128
	v_exp_f32_e32 v128, v140
	v_add_f32_e32 v120, 1.0, v120
	v_rcp_f32_e32 v130, v120
	v_exp_f32_e32 v120, v131
	v_add_f32_e32 v128, 1.0, v128
	v_rcp_f32_e32 v140, v128
	v_exp_f32_e32 v128, v141
	v_add_f32_e32 v120, 1.0, v120
	v_mul_f32_e32 v125, v125, v121
	v_rcp_f32_e32 v131, v120
	v_add_f32_e32 v128, 1.0, v128
	v_mov_b32_e32 v120, v122
	v_mov_b32_e32 v121, v183
	v_mul_f32_e32 v133, v133, v129
	v_rcp_f32_e32 v141, v128
	v_pk_mul_f32 v[128:129], v[126:127], v[136:137] op_sel_hi:[1,0]
	v_pk_mul_f32 v[120:121], v[182:183], v[120:121]
	v_exp_f32_e32 v128, v128
	v_mul_f32_e32 v122, v132, v121
	v_mul_f32_e32 v126, v133, v121
	v_mul_f32_e32 v132, v134, v121
	v_mul_f32_e32 v133, v135, v121
	v_mul_f32_e32 v124, v124, v121
	v_mul_f32_e32 v125, v125, v121
	v_mul_f32_e32 v120, v120, v121
	v_mul_f32_e32 v121, v123, v121
	v_exp_f32_e32 v123, v129
	v_add_f32_e32 v128, 1.0, v128
	v_rcp_f32_e32 v128, v128
	v_mul_f32_e32 v122, v122, v138
	v_add_f32_e32 v123, 1.0, v123
	v_rcp_f32_e32 v123, v123
	v_mul_f32_e32 v124, v124, v130
	v_mul_f32_e32 v125, v125, v131
	v_mul_f32_e32 v120, v120, v128
	v_mul_f32_e32 v121, v121, v123
	v_mul_f32_e32 v126, v126, v142
	v_mul_f32_e32 v132, v132, v140
	v_mul_f32_e32 v133, v133, v141
	v_cvt_pk_bf16_f32 v122, v122, v126
	v_cvt_pk_bf16_f32 v123, v132, v133
	v_cvt_pk_bf16_f32 v124, v124, v125
	v_cvt_pk_bf16_f32 v125, v120, v121
	v_mov_b64_e32 v[120:121], s[40:41]
	v_mad_i64_i32 v[126:127], s[40:41], v180, s75, v[120:121]
	s_lshl_b32 s40, s74, 7
	s_ashr_i32 s41, s40, 31
	s_lshl_b64 s[40:41], s[40:41], 1
	v_lshl_add_u64 v[126:127], v[126:127], 0, s[40:41]
	v_lshl_add_u64 v[126:127], v[126:127], 0, s[96:97]
	v_lshl_add_u64 v[126:127], v[126:127], 0, v[0:1]
	global_store_dwordx4 v[126:127], v[122:125], off
	v_mov_b32_e32 v180, v110
	v_mov_b32_e32 v144, v46
	v_mul_f32_e32 v122, 0xbfb8aa3b, v181
	v_pk_mul_f32 v[126:127], v[116:117], v[122:123] op_sel_hi:[1,0]
	v_mul_f32_e32 v116, v116, v112
	v_exp_f32_e32 v112, v126
	v_pk_mul_f32 v[124:125], v[118:119], v[122:123] op_sel_hi:[1,0]
	v_mul_f32_e32 v118, v118, v114
	v_mul_f32_e32 v119, v119, v115
	v_add_f32_e32 v112, 1.0, v112
	v_rcp_f32_e32 v123, v112
	v_exp_f32_e32 v112, v127
	v_mul_f32_e32 v117, v117, v113
	v_mov_b32_e32 v138, v30
	v_pk_mul_f32 v[114:115], v[108:109], v[122:123] op_sel_hi:[1,0]
; __device__ __forceinline__ unsigned cvt_pk_bf16(float lo, float hi) { unsigned r; asm volatile("v_cvt_pk_bf16_f32 %0, %1, %2" : "=v"(r) : "v"(lo), "v"(hi)); return r; }
;     __device__ __forceinline__ void operator()(const f32x4 (&acc)[2][2][4][2], const Unit& u, int wr, int wc, int fr, int fq) const {
;     ...
;             for (int m = 0; m < 4; ++m) {
;                 const int row = u.pm * BM + ai * HALF + wr * 64 + m * 16 + fr;
;                 const float rs = rs8[ai][m], rsl = -1.4426950408889634f * rs, rs2 = rs * rs;
;                 float hv[8];
; #pragma unroll
;                 for (int n = 0; n < 2; ++n) {
;                     const f32x4 ag = acc[ai][0][m][n], au = acc[ai][1][m][n];
;                     const f32x4 ea = ag * rsl, gu = (ag * au) * rs2;
; #pragma unroll
;                     for (int j = 0; j < 4; ++j) hv[4 * n + j] = gu[j] * __builtin_amdgcn_rcpf(1.0f + __builtin_amdgcn_exp2f(ea[j]));
;                 }
;                 u32x4 w; w.x = cvt_pk_bf16(hv[0], hv[1]); w.y = cvt_pk_bf16(hv[2], hv[3]); w.z = cvt_pk_bf16(hv[4], hv[5]); w.w = cvt_pk_bf16(hv[6], hv[7]);
;                 *(u32x4*)(H + (size_t)row * ldh + u.pn * 128 + wc * 32 + 8 * fq) = w;
	v_add_f32_e32 v112, 1.0, v112
	v_rcp_f32_e32 v126, v112
	v_exp_f32_e32 v112, v124
	v_mul_f32_e32 v108, v108, v104
	v_exp_f32_e32 v104, v114
	v_mul_f32_e32 v109, v109, v105
	v_add_f32_e32 v112, 1.0, v112
	v_rcp_f32_e32 v124, v112
	v_exp_f32_e32 v112, v125
	v_add_f32_e32 v104, 1.0, v104
	v_rcp_f32_e32 v114, v104
	v_exp_f32_e32 v104, v115
	v_add_f32_e32 v112, 1.0, v112
	v_rcp_f32_e32 v125, v112
	v_pk_mul_f32 v[112:113], v[110:111], v[122:123] op_sel_hi:[1,0]
	v_add_f32_e32 v104, 1.0, v104
	v_exp_f32_e32 v112, v112
	v_rcp_f32_e32 v115, v104
	v_mov_b32_e32 v104, v106
	v_mov_b32_e32 v105, v181
	v_add_f32_e32 v112, 1.0, v112
	v_rcp_f32_e32 v112, v112
	v_pk_mul_f32 v[104:105], v[180:181], v[104:105]
	v_mov_b32_e32 v136, v14
	v_mul_f32_e32 v104, v104, v105
	v_mul_f32_e32 v112, v104, v112
	v_mul_f32_e32 v104, v111, v107
	v_mul_f32_e32 v106, v116, v105
	v_mul_f32_e32 v110, v117, v105
	v_mul_f32_e32 v116, v118, v105
	v_mul_f32_e32 v117, v119, v105
	v_mul_f32_e32 v108, v108, v105
	v_mul_f32_e32 v109, v109, v105
	v_mul_f32_e32 v104, v104, v105
	v_exp_f32_e32 v105, v113
	v_mul_f32_e32 v106, v106, v123
	v_mul_f32_e32 v108, v108, v114
	v_mul_f32_e32 v109, v109, v115
	v_add_f32_e32 v105, 1.0, v105
	v_rcp_f32_e32 v105, v105
	v_add_u32_e32 v111, s47, v188
	v_mul_f32_e32 v110, v110, v126
	v_mul_f32_e32 v116, v116, v124
	v_mul_f32_e32 v117, v117, v125
	v_mul_f32_e32 v107, v104, v105
	v_cvt_pk_bf16_f32 v104, v106, v110
	v_cvt_pk_bf16_f32 v105, v116, v117
	v_cvt_pk_bf16_f32 v106, v108, v109
	v_mad_i64_i32 v[108:109], s[54:55], v111, s75, v[120:121]
	v_lshl_add_u64 v[108:109], v[108:109], 0, s[40:41]
	v_lshl_add_u64 v[108:109], v[108:109], 0, s[96:97]
	v_lshl_add_u64 v[108:109], v[108:109], 0, v[0:1]
	v_cvt_pk_bf16_f32 v107, v112, v107
	global_store_dwordx4 v[108:109], v[104:107], off
	s_andn2_b64 vcc, exec, s[38:39]
	s_nop 0
	v_mul_f32_e32 v104, 0xbfb8aa3b, v155
	v_pk_mul_f32 v[108:109], v[100:101], v[104:105] op_sel_hi:[1,0]
	v_mul_f32_e32 v100, v100, v96
	v_exp_f32_e32 v96, v108
	v_pk_mul_f32 v[106:107], v[102:103], v[104:105] op_sel_hi:[1,0]
	v_mul_f32_e32 v102, v102, v98
	v_mul_f32_e32 v103, v103, v99
	v_add_f32_e32 v96, 1.0, v96
	v_rcp_f32_e32 v105, v96
	v_exp_f32_e32 v96, v109
	v_mul_f32_e32 v101, v101, v97
	v_pk_mul_f32 v[98:99], v[92:93], v[104:105] op_sel_hi:[1,0]
	v_add_f32_e32 v96, 1.0, v96
	v_rcp_f32_e32 v108, v96
	v_exp_f32_e32 v96, v106
	v_mul_f32_e32 v92, v92, v88
	v_exp_f32_e32 v88, v98
	v_mul_f32_e32 v93, v93, v89
	v_add_f32_e32 v96, 1.0, v96
	v_rcp_f32_e32 v106, v96
	v_exp_f32_e32 v96, v107
	v_add_f32_e32 v88, 1.0, v88
	v_rcp_f32_e32 v98, v88
	v_exp_f32_e32 v88, v99
	v_add_f32_e32 v96, 1.0, v96
	v_rcp_f32_e32 v107, v96
	v_pk_mul_f32 v[96:97], v[94:95], v[104:105] op_sel_hi:[1,0]
	v_add_f32_e32 v88, 1.0, v88
	v_exp_f32_e32 v96, v96
	v_rcp_f32_e32 v99, v88
	v_mov_b32_e32 v88, v90
	v_mov_b32_e32 v89, v155
	v_add_f32_e32 v96, 1.0, v96
	v_rcp_f32_e32 v96, v96
	v_pk_mul_f32 v[88:89], v[154:155], v[88:89]
	s_nop 0
	v_mul_f32_e32 v88, v88, v89
	v_mul_f32_e32 v96, v88, v96
	v_mul_f32_e32 v88, v95, v91
	v_mul_f32_e32 v90, v100, v89
	v_mul_f32_e32 v94, v101, v89
	v_mul_f32_e32 v100, v102, v89
	v_mul_f32_e32 v101, v103, v89
	v_mul_f32_e32 v92, v92, v89
	v_mul_f32_e32 v93, v93, v89
	v_mul_f32_e32 v88, v88, v89
	v_exp_f32_e32 v89, v97
	v_mul_f32_e32 v90, v90, v105
	v_mul_f32_e32 v92, v92, v98
	v_mul_f32_e32 v93, v93, v99
	v_add_f32_e32 v89, 1.0, v89
	v_rcp_f32_e32 v89, v89
	v_add_u32_e32 v95, s47, v189
	v_mul_f32_e32 v94, v94, v108
	v_mul_f32_e32 v100, v100, v106
	v_mul_f32_e32 v101, v101, v107
	v_mul_f32_e32 v91, v88, v89
	v_cvt_pk_bf16_f32 v88, v90, v94
	v_cvt_pk_bf16_f32 v89, v100, v101
	v_cvt_pk_bf16_f32 v90, v92, v93
	v_mad_i64_i32 v[92:93], s[54:55], v95, s75, v[120:121]
	v_lshl_add_u64 v[92:93], v[92:93], 0, s[40:41]
	v_lshl_add_u64 v[92:93], v[92:93], 0, s[96:97]
	v_lshl_add_u64 v[92:93], v[92:93], 0, v[0:1]
	v_cvt_pk_bf16_f32 v91, v96, v91
	global_store_dwordx4 v[92:93], v[88:91], off
	s_nop 1
	v_mul_f32_e32 v88, 0xbfb8aa3b, v153
	v_pk_mul_f32 v[92:93], v[84:85], v[88:89] op_sel_hi:[1,0]
	v_mul_f32_e32 v84, v84, v80
	v_exp_f32_e32 v80, v92
	v_pk_mul_f32 v[90:91], v[86:87], v[88:89] op_sel_hi:[1,0]
	v_mul_f32_e32 v86, v86, v82
	v_mul_f32_e32 v87, v87, v83
	v_add_f32_e32 v80, 1.0, v80
	v_rcp_f32_e32 v89, v80
	v_exp_f32_e32 v80, v93
	v_mul_f32_e32 v85, v85, v81
	v_pk_mul_f32 v[82:83], v[76:77], v[88:89] op_sel_hi:[1,0]
	v_add_f32_e32 v80, 1.0, v80
	v_rcp_f32_e32 v92, v80
	v_exp_f32_e32 v80, v90
	v_mul_f32_e32 v76, v76, v72
	v_exp_f32_e32 v72, v82
	v_mul_f32_e32 v77, v77, v73
	v_add_f32_e32 v80, 1.0, v80
	v_rcp_f32_e32 v90, v80
	v_exp_f32_e32 v80, v91
	v_add_f32_e32 v72, 1.0, v72
	v_rcp_f32_e32 v82, v72
	v_exp_f32_e32 v72, v83
	v_add_f32_e32 v80, 1.0, v80
	v_rcp_f32_e32 v91, v80
	v_pk_mul_f32 v[80:81], v[78:79], v[88:89] op_sel_hi:[1,0]
	v_add_f32_e32 v72, 1.0, v72
	v_exp_f32_e32 v80, v80
	v_rcp_f32_e32 v83, v72
	v_mov_b32_e32 v72, v74
	v_mov_b32_e32 v73, v153
	v_add_f32_e32 v80, 1.0, v80
	v_rcp_f32_e32 v80, v80
	v_pk_mul_f32 v[72:73], v[152:153], v[72:73]
	s_nop 0
	v_mul_f32_e32 v72, v72, v73
	v_mul_f32_e32 v80, v72, v80
	v_mul_f32_e32 v72, v79, v75
	v_mul_f32_e32 v74, v84, v73
	v_mul_f32_e32 v78, v85, v73
	v_mul_f32_e32 v84, v86, v73
	v_mul_f32_e32 v85, v87, v73
	v_mul_f32_e32 v76, v76, v73
	v_mul_f32_e32 v77, v77, v73
	v_mul_f32_e32 v72, v72, v73
	v_exp_f32_e32 v73, v81
	v_mul_f32_e32 v74, v74, v89
	v_mul_f32_e32 v76, v76, v82
	v_mul_f32_e32 v77, v77, v83
	v_add_f32_e32 v73, 1.0, v73
	v_rcp_f32_e32 v73, v73
	v_add_u32_e32 v79, s47, v190
	v_mul_f32_e32 v78, v78, v92
	v_mul_f32_e32 v84, v84, v90
	v_mul_f32_e32 v85, v85, v91
	v_mul_f32_e32 v75, v72, v73
; __device__ __forceinline__ unsigned cvt_pk_bf16(float lo, float hi) { unsigned r; asm volatile("v_cvt_pk_bf16_f32 %0, %1, %2" : "=v"(r) : "v"(lo), "v"(hi)); return r; }
;     __device__ __forceinline__ void operator()(const f32x4 (&acc)[2][2][4][2], const Unit& u, int wr, int wc, int fr, int fq) const {
;     ...
;             for (int m = 0; m < 4; ++m) {
;                 const int row = u.pm * BM + ai * HALF + wr * 64 + m * 16 + fr;
;                 const float rs = rs8[ai][m], rsl = -1.4426950408889634f * rs, rs2 = rs * rs;
;                 float hv[8];
; #pragma unroll
;                 for (int n = 0; n < 2; ++n) {
;                     const f32x4 ag = acc[ai][0][m][n], au = acc[ai][1][m][n];
;                     const f32x4 ea = ag * rsl, gu = (ag * au) * rs2;
; #pragma unroll
;                     for (int j = 0; j < 4; ++j) hv[4 * n + j] = gu[j] * __builtin_amdgcn_rcpf(1.0f + __builtin_amdgcn_exp2f(ea[j]));
;                 }
;                 u32x4 w; w.x = cvt_pk_bf16(hv[0], hv[1]); w.y = cvt_pk_bf16(hv[2], hv[3]); w.z = cvt_pk_bf16(hv[4], hv[5]); w.w = cvt_pk_bf16(hv[6], hv[7]);
;                 *(u32x4*)(H + (size_t)row * ldh + u.pn * 128 + wc * 32 + 8 * fq) = w;
	v_cvt_pk_bf16_f32 v72, v74, v78
	v_cvt_pk_bf16_f32 v73, v84, v85
	v_cvt_pk_bf16_f32 v74, v76, v77
	v_mad_i64_i32 v[76:77], s[54:55], v79, s75, v[120:121]
	v_lshl_add_u64 v[76:77], v[76:77], 0, s[40:41]
	v_lshl_add_u64 v[76:77], v[76:77], 0, s[96:97]
	v_lshl_add_u64 v[76:77], v[76:77], 0, v[0:1]
	v_cvt_pk_bf16_f32 v75, v80, v75
	global_store_dwordx4 v[76:77], v[72:75], off
	s_nop 1
	v_mul_f32_e32 v72, 0xbfb8aa3b, v147
	v_pk_mul_f32 v[76:77], v[68:69], v[72:73] op_sel_hi:[1,0]
	v_mul_f32_e32 v68, v68, v64
	v_exp_f32_e32 v64, v76
	v_pk_mul_f32 v[74:75], v[70:71], v[72:73] op_sel_hi:[1,0]
	v_mul_f32_e32 v70, v70, v66
	v_mul_f32_e32 v71, v71, v67
	v_add_f32_e32 v64, 1.0, v64
	v_rcp_f32_e32 v73, v64
	v_exp_f32_e32 v64, v77
	v_mul_f32_e32 v69, v69, v65
	v_pk_mul_f32 v[66:67], v[60:61], v[72:73] op_sel_hi:[1,0]
	v_add_f32_e32 v64, 1.0, v64
	v_rcp_f32_e32 v76, v64
	v_exp_f32_e32 v64, v74
	v_mul_f32_e32 v60, v60, v56
	v_exp_f32_e32 v56, v66
	v_mul_f32_e32 v61, v61, v57
	v_add_f32_e32 v64, 1.0, v64
	v_rcp_f32_e32 v74, v64
	v_exp_f32_e32 v64, v75
	v_add_f32_e32 v56, 1.0, v56
	v_rcp_f32_e32 v66, v56
	v_exp_f32_e32 v56, v67
	v_add_f32_e32 v64, 1.0, v64
	v_rcp_f32_e32 v75, v64
	v_pk_mul_f32 v[64:65], v[62:63], v[72:73] op_sel_hi:[1,0]
	v_add_f32_e32 v56, 1.0, v56
	v_exp_f32_e32 v64, v64
	v_rcp_f32_e32 v67, v56
	v_mov_b32_e32 v56, v58
	v_mov_b32_e32 v57, v147
	v_add_f32_e32 v64, 1.0, v64
	v_rcp_f32_e32 v64, v64
	v_pk_mul_f32 v[56:57], v[146:147], v[56:57]
	s_nop 0
	v_mul_f32_e32 v56, v56, v57
	v_mul_f32_e32 v64, v56, v64
	v_mul_f32_e32 v56, v63, v59
	v_mul_f32_e32 v58, v68, v57
	v_mul_f32_e32 v62, v69, v57
	v_mul_f32_e32 v68, v70, v57
	v_mul_f32_e32 v69, v71, v57
	v_mul_f32_e32 v60, v60, v57
	v_mul_f32_e32 v61, v61, v57
	v_mul_f32_e32 v56, v56, v57
	v_exp_f32_e32 v57, v65
	v_mul_f32_e32 v58, v58, v73
	v_mul_f32_e32 v60, v60, v66
	v_mul_f32_e32 v61, v61, v67
	v_add_f32_e32 v57, 1.0, v57
	v_rcp_f32_e32 v57, v57
	v_mul_f32_e32 v62, v62, v76
	v_mul_f32_e32 v68, v68, v74
	v_mul_f32_e32 v69, v69, v75
	v_mul_f32_e32 v59, v56, v57
	v_cvt_pk_bf16_f32 v56, v58, v62
	v_cvt_pk_bf16_f32 v57, v68, v69
	v_cvt_pk_bf16_f32 v58, v60, v61
	v_mad_i64_i32 v[60:61], s[54:55], v178, s75, v[120:121]
	v_lshl_add_u64 v[60:61], v[60:61], 0, s[40:41]
	v_lshl_add_u64 v[60:61], v[60:61], 0, s[96:97]
	v_lshl_add_u64 v[60:61], v[60:61], 0, v[0:1]
	v_cvt_pk_bf16_f32 v59, v64, v59
	global_store_dwordx4 v[60:61], v[56:59], off
	s_nop 1
	v_mul_f32_e32 v56, 0xbfb8aa3b, v145
	v_pk_mul_f32 v[60:61], v[52:53], v[56:57] op_sel_hi:[1,0]
	v_mul_f32_e32 v52, v52, v48
	v_exp_f32_e32 v48, v60
	v_pk_mul_f32 v[58:59], v[54:55], v[56:57] op_sel_hi:[1,0]
	v_mul_f32_e32 v54, v54, v50
	v_mul_f32_e32 v55, v55, v51
	v_add_f32_e32 v48, 1.0, v48
	v_rcp_f32_e32 v57, v48
	v_exp_f32_e32 v48, v61
	v_mul_f32_e32 v53, v53, v49
	v_pk_mul_f32 v[50:51], v[44:45], v[56:57] op_sel_hi:[1,0]
	v_add_f32_e32 v48, 1.0, v48
	v_rcp_f32_e32 v60, v48
	v_exp_f32_e32 v48, v58
	v_mul_f32_e32 v44, v44, v40
	v_exp_f32_e32 v40, v50
	v_mul_f32_e32 v45, v45, v41
	v_add_f32_e32 v48, 1.0, v48
	v_rcp_f32_e32 v58, v48
	v_exp_f32_e32 v48, v59
	v_add_f32_e32 v40, 1.0, v40
	v_rcp_f32_e32 v50, v40
	v_exp_f32_e32 v40, v51
	v_add_f32_e32 v48, 1.0, v48
	v_rcp_f32_e32 v59, v48
	v_pk_mul_f32 v[48:49], v[46:47], v[56:57] op_sel_hi:[1,0]
	v_add_f32_e32 v40, 1.0, v40
	v_exp_f32_e32 v48, v48
	v_rcp_f32_e32 v51, v40
	v_mov_b32_e32 v40, v42
	v_mov_b32_e32 v41, v145
	v_add_f32_e32 v48, 1.0, v48
	v_rcp_f32_e32 v48, v48
	v_pk_mul_f32 v[40:41], v[144:145], v[40:41]
	s_nop 0
	v_mul_f32_e32 v40, v40, v41
	v_mul_f32_e32 v48, v40, v48
	v_mul_f32_e32 v40, v47, v43
	v_mul_f32_e32 v42, v52, v41
	v_mul_f32_e32 v46, v53, v41
	v_mul_f32_e32 v52, v54, v41
	v_mul_f32_e32 v53, v55, v41
	v_mul_f32_e32 v44, v44, v41
	v_mul_f32_e32 v45, v45, v41
	v_mul_f32_e32 v40, v40, v41
	v_exp_f32_e32 v41, v49
	v_mul_f32_e32 v42, v42, v57
	v_mul_f32_e32 v44, v44, v50
	v_mul_f32_e32 v45, v45, v51
	v_add_f32_e32 v41, 1.0, v41
	v_rcp_f32_e32 v41, v41
	v_mul_f32_e32 v46, v46, v60
	v_mul_f32_e32 v52, v52, v58
	v_mul_f32_e32 v53, v53, v59
	v_mul_f32_e32 v43, v40, v41
	v_cvt_pk_bf16_f32 v40, v42, v46
	v_cvt_pk_bf16_f32 v41, v52, v53
	v_cvt_pk_bf16_f32 v42, v44, v45
	v_mad_i64_i32 v[44:45], s[54:55], v176, s75, v[120:121]
	v_lshl_add_u64 v[44:45], v[44:45], 0, s[40:41]
	v_lshl_add_u64 v[44:45], v[44:45], 0, s[96:97]
; __device__ __forceinline__ unsigned cvt_pk_bf16(float lo, float hi) { unsigned r; asm volatile("v_cvt_pk_bf16_f32 %0, %1, %2" : "=v"(r) : "v"(lo), "v"(hi)); return r; }
; #define PG8_BAR __builtin_amdgcn_s_barrier()
;     __device__ __forceinline__ void operator()(const f32x4 (&acc)[2][2][4][2], const Unit& u, int wr, int wc, int fr, int fq) const {
;     ...
;                 const float rs = rs8[ai][m], rsl = -1.4426950408889634f * rs, rs2 = rs * rs;
;                 float hv[8];
; #pragma unroll
;                 for (int n = 0; n < 2; ++n) {
;                     const f32x4 ag = acc[ai][0][m][n], au = acc[ai][1][m][n];
;                     const f32x4 ea = ag * rsl, gu = (ag * au) * rs2;
; #pragma unroll
;                     for (int j = 0; j < 4; ++j) hv[4 * n + j] = gu[j] * __builtin_amdgcn_rcpf(1.0f + __builtin_amdgcn_exp2f(ea[j]));
;                 }
;                 u32x4 w; w.x = cvt_pk_bf16(hv[0], hv[1]); w.y = cvt_pk_bf16(hv[2], hv[3]); w.z = cvt_pk_bf16(hv[4], hv[5]); w.w = cvt_pk_bf16(hv[6], hv[7]);
;                 *(u32x4*)(H + (size_t)row * ldh + u.pn * 128 + wc * 32 + 8 * fq) = w;
; template <class Epi, class Sched, bool ALIGN_EPI = false, bool SP2 = false>
; __device__ __forceinline__ void gemm_phase(PG8_LAS unsigned char* lds, const Gemm g, const Sched& S, const Epi& E) {
;     ...
;         if constexpr (ALIGN_EPI) { if (wr == 0) PG8_BAR; }
;         if constexpr (!Epi::AFTER_DRAIN) { E(acc, cur, wr, wc, fr, fq); S.done(cur); }
;         if (!has_next) break;
; #pragma unroll
;         for (int a = 0; a < 2; ++a)
; #pragma unroll
;             for (int b = 0; b < 2; ++b)
; #pragma unroll
;                 for (int m = 0; m < 4; ++m)
; #pragma unroll
;                     for (int n = 0; n < 2; ++n) acc[a][b][m][n] = (f32x4){0.f, 0.f, 0.f, 0.f};
;         cur = nxt; cA = nA; cB = nB; ++ui;
;         if constexpr (ALIGN_EPI) { if (wr == 1) PG8_BAR; }
	v_lshl_add_u64 v[44:45], v[44:45], 0, v[0:1]
	v_cvt_pk_bf16_f32 v43, v48, v43
	global_store_dwordx4 v[44:45], v[40:43], off
	s_nop 1
	v_mul_f32_e32 v40, 0xbfb8aa3b, v139
	v_pk_mul_f32 v[44:45], v[36:37], v[40:41] op_sel_hi:[1,0]
	v_mul_f32_e32 v36, v36, v32
	v_exp_f32_e32 v32, v44
	v_pk_mul_f32 v[42:43], v[38:39], v[40:41] op_sel_hi:[1,0]
	v_mul_f32_e32 v38, v38, v34
	v_mul_f32_e32 v39, v39, v35
	v_add_f32_e32 v32, 1.0, v32
	v_rcp_f32_e32 v41, v32
	v_exp_f32_e32 v32, v45
	v_mul_f32_e32 v37, v37, v33
	v_pk_mul_f32 v[34:35], v[28:29], v[40:41] op_sel_hi:[1,0]
	v_add_f32_e32 v32, 1.0, v32
	v_rcp_f32_e32 v44, v32
	v_exp_f32_e32 v32, v42
	v_mul_f32_e32 v28, v28, v24
	v_exp_f32_e32 v24, v34
	v_mul_f32_e32 v29, v29, v25
	v_add_f32_e32 v32, 1.0, v32
	v_rcp_f32_e32 v42, v32
	v_exp_f32_e32 v32, v43
	v_add_f32_e32 v24, 1.0, v24
	v_rcp_f32_e32 v34, v24
	v_exp_f32_e32 v24, v35
	v_add_f32_e32 v32, 1.0, v32
	v_rcp_f32_e32 v43, v32
	v_pk_mul_f32 v[32:33], v[30:31], v[40:41] op_sel_hi:[1,0]
	v_add_f32_e32 v24, 1.0, v24
	v_exp_f32_e32 v32, v32
	v_rcp_f32_e32 v35, v24
	v_mov_b32_e32 v24, v26
	v_mov_b32_e32 v25, v139
	v_add_f32_e32 v32, 1.0, v32
	v_rcp_f32_e32 v32, v32
	v_pk_mul_f32 v[24:25], v[138:139], v[24:25]
	s_nop 0
	v_mul_f32_e32 v24, v24, v25
	v_mul_f32_e32 v32, v24, v32
	v_mul_f32_e32 v24, v31, v27
	v_mul_f32_e32 v26, v36, v25
	v_mul_f32_e32 v30, v37, v25
	v_mul_f32_e32 v36, v38, v25
	v_mul_f32_e32 v37, v39, v25
	v_mul_f32_e32 v28, v28, v25
	v_mul_f32_e32 v29, v29, v25
	v_mul_f32_e32 v24, v24, v25
	v_exp_f32_e32 v25, v33
	v_mul_f32_e32 v26, v26, v41
	v_mul_f32_e32 v28, v28, v34
	v_mul_f32_e32 v29, v29, v35
	v_add_f32_e32 v25, 1.0, v25
	v_rcp_f32_e32 v25, v25
	v_mul_f32_e32 v30, v30, v44
	v_mul_f32_e32 v36, v36, v42
	v_mul_f32_e32 v37, v37, v43
	v_mul_f32_e32 v27, v24, v25
	v_cvt_pk_bf16_f32 v24, v26, v30
	v_cvt_pk_bf16_f32 v25, v36, v37
	v_cvt_pk_bf16_f32 v26, v28, v29
	v_mad_i64_i32 v[28:29], s[54:55], v174, s75, v[120:121]
	v_lshl_add_u64 v[28:29], v[28:29], 0, s[40:41]
	v_lshl_add_u64 v[28:29], v[28:29], 0, s[96:97]
	v_lshl_add_u64 v[28:29], v[28:29], 0, v[0:1]
	v_cvt_pk_bf16_f32 v27, v32, v27
	global_store_dwordx4 v[28:29], v[24:27], off
	s_nop 1
	v_mul_f32_e32 v24, 0xbfb8aa3b, v137
	v_pk_mul_f32 v[28:29], v[20:21], v[24:25] op_sel_hi:[1,0]
	v_mul_f32_e32 v20, v20, v16
	v_exp_f32_e32 v16, v28
	v_pk_mul_f32 v[26:27], v[22:23], v[24:25] op_sel_hi:[1,0]
	v_mul_f32_e32 v22, v22, v18
	v_mul_f32_e32 v23, v23, v19
	v_add_f32_e32 v16, 1.0, v16
	v_rcp_f32_e32 v25, v16
	v_exp_f32_e32 v16, v29
	v_mul_f32_e32 v21, v21, v17
	v_pk_mul_f32 v[18:19], v[12:13], v[24:25] op_sel_hi:[1,0]
	v_add_f32_e32 v16, 1.0, v16
	v_rcp_f32_e32 v28, v16
	v_exp_f32_e32 v16, v26
	v_mul_f32_e32 v12, v12, v8
	v_exp_f32_e32 v8, v18
	v_mul_f32_e32 v13, v13, v9
	v_add_f32_e32 v16, 1.0, v16
	v_rcp_f32_e32 v26, v16
	v_exp_f32_e32 v16, v27
	v_add_f32_e32 v8, 1.0, v8
	v_rcp_f32_e32 v18, v8
	v_exp_f32_e32 v8, v19
	v_add_f32_e32 v16, 1.0, v16
	v_rcp_f32_e32 v27, v16
	v_pk_mul_f32 v[16:17], v[14:15], v[24:25] op_sel_hi:[1,0]
	v_add_f32_e32 v8, 1.0, v8
	v_exp_f32_e32 v16, v16
	v_rcp_f32_e32 v19, v8
	v_mov_b32_e32 v8, v10
	v_mov_b32_e32 v9, v137
	v_add_f32_e32 v16, 1.0, v16
	v_rcp_f32_e32 v16, v16
	v_pk_mul_f32 v[8:9], v[136:137], v[8:9]
	s_nop 0
	v_mul_f32_e32 v8, v8, v9
	v_mul_f32_e32 v16, v8, v16
	v_mul_f32_e32 v8, v15, v11
	v_mul_f32_e32 v10, v20, v9
	v_mul_f32_e32 v14, v21, v9
	v_mul_f32_e32 v20, v22, v9
	v_mul_f32_e32 v21, v23, v9
	v_mul_f32_e32 v12, v12, v9
	v_mul_f32_e32 v13, v13, v9
	v_mul_f32_e32 v8, v8, v9
	v_exp_f32_e32 v9, v17
	v_mul_f32_e32 v10, v10, v25
	v_mul_f32_e32 v12, v12, v18
	v_mul_f32_e32 v13, v13, v19
	v_add_f32_e32 v9, 1.0, v9
	v_rcp_f32_e32 v9, v9
	v_mul_f32_e32 v14, v14, v28
	v_mul_f32_e32 v20, v20, v26
	v_mul_f32_e32 v21, v21, v27
	v_mul_f32_e32 v11, v8, v9
	v_cvt_pk_bf16_f32 v8, v10, v14
	v_cvt_pk_bf16_f32 v9, v20, v21
	v_cvt_pk_bf16_f32 v10, v12, v13
	v_mad_i64_i32 v[12:13], s[54:55], v172, s75, v[120:121]
	v_lshl_add_u64 v[12:13], v[12:13], 0, s[40:41]
	v_lshl_add_u64 v[12:13], v[12:13], 0, s[96:97]
	v_lshl_add_u64 v[12:13], v[12:13], 0, v[0:1]
	s_mov_b64 s[40:41], -1
	v_cvt_pk_bf16_f32 v11, v16, v11
	global_store_dwordx4 v[12:13], v[8:11], off
	s_cbranch_vccnz .LBB0_564
	s_andn2_b64 vcc, exec, s[42:43]
	s_cbranch_vccnz .LBB0_563
	s_barrier
	s_branch .LBB0_563
